# adaLN items of layers 2,3 deferred from the prologue to the out-proj phases' idle workgroups (P0 reads 25 MB less)
# baseline (speedup 1.0000x reference)
.LBB0_1159:
	s_cmp_lt_i32 s73, 16
	s_cselect_b64 s[2:3], -1, 0
	s_waitcnt lgkmcnt(0)
	v_readlane_b32 s4, v254, 17
	s_and_b64 s[2:3], s[52:53], s[2:3]
	v_readlane_b32 s5, v254, 18
	s_and_b64 s[2:3], s[4:5], s[2:3]
	s_andn2_b64 vcc, exec, s[2:3]
	s_cbranch_vccnz .LBB0_1298
	s_cmp_gt_u32 s58, 1
	s_cbranch_scc1 .Lada_skip
	s_lshl_b32 s27, s58, 6
	s_add_i32 s27, s27, s63
	s_add_i32 s27, s27, 0xffffffc0
	s_mov_b32 s26, s38
	s_mov_b32 s98, 1
	s_movk_i32 s99, 0xff
	s_branch .Lada_entry
.Lada_ret:
	s_mov_b32 s98, 0
.Lada_skip:
	s_add_i32 s2, s38, 0xffffff40
	v_readlane_b32 s3, v254, 19
	s_mov_b32 s4, s75
	s_waitcnt vmcnt(0)
	v_mbcnt_lo_u32_b32 v1, -1, 0
	v_mbcnt_hi_u32_b32 v1, -1, v1
	s_add_i32 s14, s58, 1
	v_lshl_add_u32 v0, s4, 6, v1
	v_ashrrev_i32_e32 v0, 6, v0
	v_lshl_add_u32 v3, s3, 3, v0
	s_mul_hi_i32 s3, s14, 0x55555556
	s_lshr_b32 s4, s3, 31
	s_add_i32 s3, s3, s4
	s_mul_i32 s4, s3, 3
	s_sub_i32 s30, s14, s4
	s_cmp_eq_u32 s30, 0
	s_movk_i32 s4, 0x8a0
	s_cselect_b32 s31, s4, 0x700
	v_cmp_gt_i32_e32 vcc, s31, v3
	s_and_saveexec_b64 s[4:5], vcc
	s_cbranch_execz .LBB0_1265
	v_lshlrev_b32_e32 v4, 2, v1
	v_lshl_add_u32 v7, v0, 14, 0
	v_bfe_u32 v0, v1, 5, 1
	v_and_b32_e32 v2, 31, v1
	v_bfe_u32 v5, v1, 3, 3
	v_and_b32_e32 v6, 28, v4
	v_and_b32_e32 v1, 7, v1
	s_lshl_b32 s35, s3, 8
	s_mul_i32 s36, s3, 0x120
	s_mul_i32 s37, s3, 0x380
	v_lshl_add_u32 v8, v6, 2, v7
	v_mul_u32_u24_e32 v9, 0x84, v5
	v_lshlrev_b32_e32 v4, 3, v1
	v_mul_u32_u24_e32 v1, 0x420, v1
	v_lshlrev_b32_e32 v10, 2, v5
	s_lshl_b32 s33, s2, 3
	s_add_i32 s34, s35, 0xba0
	s_addk_i32 s35, 0xaa0
	s_addk_i32 s36, 0x980
	s_addk_i32 s37, 0x600
	s_lshl_b32 s39, s14, 9
	v_lshl_add_u32 v2, v2, 2, v7
	v_add3_u32 v22, v7, v1, v10
	v_or_b32_e32 v23, 8, v5
	v_or_b32_e32 v24, 16, v5
	v_or_b32_e32 v25, 24, v5
	v_mov_b32_e32 v1, v0
	s_mov_b64 s[6:7], 0
	v_lshlrev_b32_e32 v6, 2, v6
	v_add_u32_e32 v26, v8, v9
	v_lshlrev_b32_e32 v8, 1, v4
	s_branch .LBB0_1163

.LBB0_1517:
	s_mov_b32 s27, s63
	s_waitcnt lgkmcnt(0)
	s_mov_b32 s26, s38
	s_mov_b32 s98, 0
	s_movk_i32 s99, 0x7f
.Lada_entry:
	s_mov_b32 s2, s75
	v_mbcnt_lo_u32_b32 v110, -1, 0
	v_mbcnt_hi_u32_b32 v110, -1, v110
	s_cmp_gt_i32 s27, s99
	v_lshl_add_u32 v75, s2, 6, v110
	s_cbranch_scc1 .LBB0_1536
	s_movk_i32 s3, 0x1400
	v_cmp_gt_i32_e64 s[10:11], s3, v75
	s_mov_b32 s3, 0x2aaaaaab
	s_waitcnt vmcnt(0)
	v_mul_hi_i32 v0, v75, s3
	v_ashrrev_i32_e32 v1, 1, v0
	v_lshrrev_b32_e32 v2, 31, v0
	v_add_u32_e32 v1, v1, v2
	s_movk_i32 s12, 0x3000
	v_add_u32_e32 v4, 32, v1
	v_mad_i64_i32 v[28:29], s[6:7], v4, s12, 0
	v_add_u32_e32 v4, 64, v1
	v_mad_i64_i32 v[30:31], s[6:7], v4, s12, 0
	v_add_u32_e32 v4, 0x60, v1
	v_mad_i64_i32 v[32:33], s[6:7], v4, s12, 0
	v_add_u32_e32 v4, 0x80, v1
	v_mad_i64_i32 v[34:35], s[6:7], v4, s12, 0
	v_add_u32_e32 v4, 0xa0, v1
	v_mad_i64_i32 v[36:37], s[6:7], v4, s12, 0
	v_add_u32_e32 v4, 0xc0, v1
	v_mad_i64_i32 v[38:39], s[6:7], v4, s12, 0
	v_add_u32_e32 v4, 0xe0, v1
	v_mad_i64_i32 v[40:41], s[6:7], v4, s12, 0
	v_add_u32_e32 v4, 0x100, v1
	v_mad_i64_i32 v[42:43], s[6:7], v4, s12, 0
	v_add_u32_e32 v4, 0x120, v1
	v_mad_i64_i32 v[44:45], s[6:7], v4, s12, 0
	v_add_u32_e32 v4, 0x140, v1
	v_mad_i64_i32 v[46:47], s[6:7], v4, s12, 0
	v_add_u32_e32 v4, 0x160, v1
	v_mad_i64_i32 v[48:49], s[6:7], v4, s12, 0
	v_add_u32_e32 v4, 0x180, v1
	v_mad_i64_i32 v[50:51], s[6:7], v4, s12, 0
	v_add_u32_e32 v4, 0x1a0, v1
	v_mad_i64_i32 v[52:53], s[6:7], v4, s12, 0
	v_add_u32_e32 v4, 0x1c0, v1
	v_mad_i64_i32 v[54:55], s[6:7], v4, s12, 0
	v_add_u32_e32 v4, 0x1e0, v1
	v_mad_i64_i32 v[56:57], s[6:7], v4, s12, 0
	v_add_u32_e32 v4, 0x200, v1
	v_mad_i64_i32 v[58:59], s[6:7], v4, s12, 0
	v_add_u32_e32 v4, 0x220, v1
	v_mad_i64_i32 v[60:61], s[6:7], v4, s12, 0
	v_add_u32_e32 v4, 0x240, v1
	v_mad_i64_i32 v[62:63], s[6:7], v4, s12, 0
	v_add_u32_e32 v4, 0x260, v1
	v_mad_i64_i32 v[64:65], s[6:7], v4, s12, 0
	v_add_u32_e32 v4, 0x280, v1
	v_ashrrev_i32_e32 v0, 3, v0
	v_mad_i64_i32 v[66:67], s[6:7], v4, s12, 0
	v_add_u32_e32 v4, 0x2a0, v1
	v_add_u32_e32 v74, v0, v2
	s_movk_i32 s3, 0x180
	v_mul_lo_u32 v3, v1, 12
	v_mad_i64_i32 v[68:69], s[6:7], v4, s12, 0
	v_add_u32_e32 v4, 0x2c0, v1
	v_mul_lo_u32 v0, v74, 48
	v_cmp_gt_i32_e64 s[4:5], s3, v75
	v_sub_u32_e32 v3, v75, v3
	v_mad_i64_i32 v[70:71], s[6:7], v4, s12, 0
	v_add_u32_e32 v4, 0x2e0, v1
	s_movk_i32 s3, 0x3c0
	v_sub_u32_e32 v76, v75, v0
	v_lshlrev_b32_e32 v0, 2, v110
	v_lshlrev_b32_e32 v24, 2, v3
	v_mad_i64_i32 v[26:27], s[6:7], v1, s12, 0
	v_mad_i64_i32 v[72:73], s[6:7], v4, s12, 0
	v_add_u32_e32 v4, 0x300, v1
	v_add_u32_e32 v5, 0x320, v1
	v_add_u32_e32 v6, 0x340, v1
	v_add_u32_e32 v7, 0x360, v1
	v_add_u32_e32 v8, 0x380, v1
	v_add_u32_e32 v9, 0x3a0, v1
	v_add_u32_e32 v10, 0x3c0, v1
	v_add_u32_e32 v11, 0x3e0, v1
	v_lshl_add_u32 v111, v1, 2, 0
	v_lshl_add_u32 v3, v3, 4, 0
	v_mul_lo_u32 v1, v1, s3
	s_movk_i32 s3, 0xf0
	v_lshl_add_u32 v0, s2, 8, v0
	s_add_i32 s2, 0, 0x5000
	v_ashrrev_i32_e32 v25, 31, v24
	v_cmp_gt_i32_e64 s[6:7], s3, v75
	v_ashrrev_i32_e32 v77, 31, v76
	v_cmp_eq_u32_e64 s[8:9], 0, v75
	v_add_u32_e32 v114, v3, v1
	v_add_u32_e32 v115, 0, v0
	v_add_u32_e32 v116, s2, v0
	s_mov_b32 s22, s27
	v_mad_i64_i32 v[78:79], s[2:3], v4, s12, 0
	v_mad_i64_i32 v[80:81], s[2:3], v5, s12, 0
	v_mad_i64_i32 v[82:83], s[2:3], v6, s12, 0
	v_mad_i64_i32 v[84:85], s[2:3], v7, s12, 0
	v_mad_i64_i32 v[86:87], s[2:3], v8, s12, 0
	v_mad_i64_i32 v[88:89], s[2:3], v9, s12, 0
	v_mad_i64_i32 v[90:91], s[2:3], v10, s12, 0
	v_mad_i64_i32 v[92:93], s[2:3], v11, s12, 0
	s_branch .LBB0_1520

.LBB0_1536:
	s_cmp_lg_u32 s98, 0
	s_cbranch_scc1 .Lada_ret
	s_mov_b32 s3, s27
	s_mov_b32 s2, s26
	s_mov_b32 s4, s75
	s_waitcnt vmcnt(0)
	v_mbcnt_lo_u32_b32 v1, -1, 0
	v_mbcnt_hi_u32_b32 v1, -1, v1
	s_nop 0
	v_lshl_add_u32 v0, s4, 6, v1
	v_ashrrev_i32_e32 v0, 6, v0
	v_lshl_add_u32 v3, s3, 3, v0
	s_movk_i32 s3, 0x8a0
	v_cmp_gt_i32_e32 vcc, s3, v3
	s_and_saveexec_b64 s[4:5], vcc
	s_cbranch_execz .LBB0_1620
	v_lshlrev_b32_e32 v4, 2, v1
	v_lshl_add_u32 v7, v0, 14, 0
	v_bfe_u32 v0, v1, 5, 1
	v_and_b32_e32 v2, 31, v1
	v_bfe_u32 v5, v1, 3, 3
	v_and_b32_e32 v6, 28, v4
	v_and_b32_e32 v1, 7, v1
	v_lshl_add_u32 v8, v6, 2, v7
	v_mul_u32_u24_e32 v9, 0x84, v5
	v_lshlrev_b32_e32 v4, 3, v1
	v_mul_u32_u24_e32 v1, 0x420, v1
	v_lshlrev_b32_e32 v10, 2, v5
	s_lshl_b32 s14, s2, 3
	v_lshl_add_u32 v2, v2, 2, v7
	v_add3_u32 v22, v7, v1, v10
	v_or_b32_e32 v23, 8, v5
	v_or_b32_e32 v24, 16, v5
	v_or_b32_e32 v25, 24, v5
	v_mov_b32_e32 v1, v0
	s_mov_b64 s[6:7], 0
	v_lshlrev_b32_e32 v6, 2, v6
	v_add_u32_e32 v26, v8, v9
	v_lshlrev_b32_e32 v8, 1, v4
	s_branch .LBB0_1539

	.amdhsa_kernel _Z6mk_fwd5KArgs
		.amdhsa_group_segment_fixed_size 0
		.amdhsa_private_segment_fixed_size 0
		.amdhsa_kernarg_size 488
		.amdhsa_user_sgpr_count 2
		.amdhsa_user_sgpr_dispatch_ptr 0
		.amdhsa_user_sgpr_queue_ptr 0
		.amdhsa_user_sgpr_kernarg_segment_ptr 1
		.amdhsa_user_sgpr_dispatch_id 0
		.amdhsa_user_sgpr_kernarg_preload_length 0
		.amdhsa_user_sgpr_kernarg_preload_offset 0
		.amdhsa_user_sgpr_private_segment_size 0
		.amdhsa_uses_dynamic_stack 0
		.amdhsa_enable_private_segment 0
		.amdhsa_system_sgpr_workgroup_id_x 1
		.amdhsa_system_sgpr_workgroup_id_y 0
		.amdhsa_system_sgpr_workgroup_id_z 0
		.amdhsa_system_sgpr_workgroup_info 0
		.amdhsa_system_vgpr_workitem_id 0
		.amdhsa_next_free_vgpr 256
		.amdhsa_next_free_sgpr 102
		.amdhsa_accum_offset 256
		.amdhsa_reserve_vcc 1
		.amdhsa_float_round_mode_32 0
		.amdhsa_float_round_mode_16_64 0
		.amdhsa_float_denorm_mode_32 3
		.amdhsa_float_denorm_mode_16_64 3
		.amdhsa_dx10_clamp 1
		.amdhsa_ieee_mode 1
		.amdhsa_fp16_overflow 0
		.amdhsa_tg_split 0
		.amdhsa_exception_fp_ieee_invalid_op 0
		.amdhsa_exception_fp_denorm_src 0
		.amdhsa_exception_fp_ieee_div_zero 0
		.amdhsa_exception_fp_ieee_overflow 0
		.amdhsa_exception_fp_ieee_underflow 0
		.amdhsa_exception_fp_ieee_inexact 0
		.amdhsa_exception_int_div_zero 0
	.end_amdhsa_kernel

amdhsa.kernels:
  - .agpr_count:     0
    .args:
      - .offset:         0
        .size:           232
        .value_kind:     by_value
      - .offset:         232
        .size:           4
        .value_kind:     hidden_block_count_x
      - .offset:         236
        .size:           4
        .value_kind:     hidden_block_count_y
      - .offset:         240
        .size:           4
        .value_kind:     hidden_block_count_z
      - .offset:         244
        .size:           2
        .value_kind:     hidden_group_size_x
      - .offset:         246
        .size:           2
        .value_kind:     hidden_group_size_y
      - .offset:         248
        .size:           2
        .value_kind:     hidden_group_size_z
      - .offset:         250
        .size:           2
        .value_kind:     hidden_remainder_x
      - .offset:         252
        .size:           2
        .value_kind:     hidden_remainder_y
      - .offset:         254
        .size:           2
        .value_kind:     hidden_remainder_z
      - .offset:         272
        .size:           8
        .value_kind:     hidden_global_offset_x
      - .offset:         280
        .size:           8
        .value_kind:     hidden_global_offset_y
      - .offset:         288
        .size:           8
        .value_kind:     hidden_global_offset_z
      - .offset:         296
        .size:           2
        .value_kind:     hidden_grid_dims
      - .offset:         352
        .size:           4
        .value_kind:     hidden_dynamic_lds_size
    .group_segment_fixed_size: 0
    .kernarg_segment_align: 8
    .kernarg_segment_size: 488
    .language:       OpenCL C
    .language_version:
      - 2
      - 0
    .max_flat_workgroup_size: 512
    .name:           _Z6mk_fwd5KArgs
    .private_segment_fixed_size: 0
    .sgpr_count:     108
    .sgpr_spill_count: 148
    .symbol:         _Z6mk_fwd5KArgs.kd
    .uniform_work_group_size: 1
    .uses_dynamic_stack: false
    .vgpr_count:     256
    .vgpr_spill_count: 0
    .wavefront_size: 64
